# v132 with the domain-1 stagger at the attention phase shortened from 3 to 2 sleep steps (further from the cliff at 4)
# baseline (speedup 1.0000x reference)
; #define PROBE_BEGIN(id) unsigned long long pb_t0_##id = 0; if (PROBE_SEC == (id)) pb_t0_##id = __builtin_amdgcn_s_memrealtime();
; #define PROBE_END(id) if (PROBE_SEC == (id)) { const unsigned long long pb_t1_ = __builtin_amdgcn_s_memrealtime(), pb_dt_ = pb_t1_ - pb_t0_##id; while (__builtin_amdgcn_s_memrealtime() - pb_t1_ < pb_dt_) __builtin_amdgcn_s_sleep(4); }
; __global__ void __launch_bounds__(NWAVES * 64, 2) hybrid_fwd(Args args) {
;     ...
;     if (IN(2)) { PROBE_BEGIN(23) p3_ssm_out(F); PROBE_END(23)
;         if (s3bar) seam_arrive(s3bar, bar.x, F.MISC + 10);
;         PROBE_BEGIN(22) p2_mix(F, 0); PROBE_END(22)
.LBB0_497:
	s_cmp_lg_u32 s10, 1
	s_cbranch_scc1 .Ldly_skip1
	s_mov_b32 s0, 2
